# grid barrier: the XCD leaders no longer bump their relay word (nobody reads it since the non-leaders poll the cross-XCD word), one atomic less before the closing wait
# speedup vs baseline: 1.0057x; 1.0030x over previous
.LBB0_145:
	s_or_b64 exec, exec, s[6:7]
	s_mov_b64 s[6:7], exec
	v_mbcnt_lo_u32_b32 v1, s6, 0
	v_mbcnt_hi_u32_b32 v1, s7, v1
	v_cmp_eq_u32_e32 vcc, 0, v1
	s_waitcnt vmcnt(0)
	buffer_inv sc1
	s_and_saveexec_b64 s[8:9], vcc
	s_cbranch_execz .LBB0_147
	s_bcnt1_i32_b64 s6, s[6:7]
	v_mov_b32_e32 v1, 0x2000
	v_mov_b32_e32 v2, s6
.LBB0_147:
	s_or_b64 exec, exec, s[8:9]
	s_waitcnt vmcnt(0)

.LBB0_268:
	s_or_b64 exec, exec, s[6:7]
	s_mov_b64 s[6:7], exec
	v_mbcnt_lo_u32_b32 v1, s6, 0
	v_mbcnt_hi_u32_b32 v1, s7, v1
	v_cmp_eq_u32_e32 vcc, 0, v1
	s_waitcnt vmcnt(0)
	buffer_inv sc1
	s_and_saveexec_b64 s[8:9], vcc
	s_cbranch_execz .LBB0_270
	s_bcnt1_i32_b64 s6, s[6:7]
	v_mov_b32_e32 v1, 0x2000
	v_mov_b32_e32 v2, s6
.LBB0_270:
	s_or_b64 exec, exec, s[8:9]
	s_waitcnt vmcnt(0)

.LBB0_343:
	s_or_b64 exec, exec, s[6:7]
	s_mov_b64 s[6:7], exec
	v_mbcnt_lo_u32_b32 v1, s6, 0
	v_mbcnt_hi_u32_b32 v1, s7, v1
	v_cmp_eq_u32_e32 vcc, 0, v1
	s_waitcnt vmcnt(0)
	buffer_inv sc1
	s_and_saveexec_b64 s[8:9], vcc
	s_cbranch_execz .LBB0_345
	s_bcnt1_i32_b64 s6, s[6:7]
	v_mov_b32_e32 v1, 0x2000
	v_mov_b32_e32 v2, s6
.LBB0_345:
	s_or_b64 exec, exec, s[8:9]
	s_waitcnt vmcnt(0)

.LBB0_440:
	s_or_b64 exec, exec, s[6:7]
	s_mov_b64 s[6:7], exec
	v_mbcnt_lo_u32_b32 v1, s6, 0
	v_mbcnt_hi_u32_b32 v1, s7, v1
	v_cmp_eq_u32_e32 vcc, 0, v1
	s_waitcnt vmcnt(0)
	buffer_inv sc1
	s_and_saveexec_b64 s[8:9], vcc
	s_cbranch_execz .LBB0_442
	s_bcnt1_i32_b64 s6, s[6:7]
	v_mov_b32_e32 v1, 0x2000
	v_mov_b32_e32 v2, s6
.LBB0_442:
	s_or_b64 exec, exec, s[8:9]
	s_waitcnt vmcnt(0)

.LBB0_519:
	s_or_b64 exec, exec, s[6:7]
	s_mov_b64 s[6:7], exec
	v_mbcnt_lo_u32_b32 v1, s6, 0
	v_mbcnt_hi_u32_b32 v1, s7, v1
	v_cmp_eq_u32_e32 vcc, 0, v1
	s_waitcnt vmcnt(0)
	buffer_inv sc1
	s_and_saveexec_b64 s[8:9], vcc
	s_cbranch_execz .LBB0_521
	s_bcnt1_i32_b64 s6, s[6:7]
	v_mov_b32_e32 v1, 0x2000
	v_mov_b32_e32 v2, s6
.LBB0_521:
	s_or_b64 exec, exec, s[8:9]
	s_waitcnt vmcnt(0)

.LBB0_616:
	s_or_b64 exec, exec, s[8:9]
	s_mov_b64 s[8:9], exec
	v_mbcnt_lo_u32_b32 v1, s8, 0
	v_mbcnt_hi_u32_b32 v1, s9, v1
	v_cmp_eq_u32_e32 vcc, 0, v1
	s_waitcnt vmcnt(0)
	buffer_inv sc1
	s_and_saveexec_b64 s[10:11], vcc
	s_cbranch_execz .LBB0_618
	s_bcnt1_i32_b64 s8, s[8:9]
	v_mov_b32_e32 v1, 0x2000
	v_mov_b32_e32 v2, s8
.LBB0_618:
	s_or_b64 exec, exec, s[10:11]
	s_waitcnt vmcnt(0)

.LBB0_899:
	s_or_b64 exec, exec, s[6:7]
	s_mov_b64 s[6:7], exec
	v_mbcnt_lo_u32_b32 v1, s6, 0
	v_mbcnt_hi_u32_b32 v1, s7, v1
	v_cmp_eq_u32_e32 vcc, 0, v1
	s_waitcnt vmcnt(0)
	buffer_inv sc1
	s_and_saveexec_b64 s[8:9], vcc
	s_cbranch_execz .LBB0_901
	s_bcnt1_i32_b64 s6, s[6:7]
	v_mov_b32_e32 v1, 0x2000
	v_mov_b32_e32 v2, s6
.LBB0_901:
	s_or_b64 exec, exec, s[8:9]
	s_waitcnt vmcnt(0)

.LBB0_991:
	s_or_b64 exec, exec, s[6:7]
	s_mov_b64 s[6:7], exec
	v_mbcnt_lo_u32_b32 v1, s6, 0
	v_mbcnt_hi_u32_b32 v1, s7, v1
	v_cmp_eq_u32_e32 vcc, 0, v1
	s_waitcnt vmcnt(0)
	buffer_inv sc1
	s_and_saveexec_b64 s[8:9], vcc
	s_cbranch_execz .LBB0_993
	s_bcnt1_i32_b64 s6, s[6:7]
	v_mov_b32_e32 v1, 0x2000
	v_mov_b32_e32 v2, s6
.LBB0_993:
	s_or_b64 exec, exec, s[8:9]
	s_waitcnt vmcnt(0)

.LBB0_1055:
	s_or_b64 exec, exec, s[6:7]
	s_mov_b64 s[6:7], exec
	v_mbcnt_lo_u32_b32 v1, s6, 0
	v_mbcnt_hi_u32_b32 v1, s7, v1
	v_cmp_eq_u32_e32 vcc, 0, v1
	s_waitcnt vmcnt(0)
	buffer_inv sc1
	s_and_saveexec_b64 s[8:9], vcc
	s_cbranch_execz .LBB0_1057
	s_bcnt1_i32_b64 s6, s[6:7]
	v_mov_b32_e32 v1, 0x2000
	v_mov_b32_e32 v2, s6
.LBB0_1057:
	s_or_b64 exec, exec, s[8:9]
	s_waitcnt vmcnt(0)

.LBB0_1253:
	s_or_b64 exec, exec, s[6:7]
	s_mov_b64 s[6:7], exec
	v_mbcnt_lo_u32_b32 v1, s6, 0
	v_mbcnt_hi_u32_b32 v1, s7, v1
	v_cmp_eq_u32_e32 vcc, 0, v1
	s_waitcnt vmcnt(0)
	buffer_inv sc1
	s_and_saveexec_b64 s[8:9], vcc
	s_cbranch_execz .LBB0_1255
	s_bcnt1_i32_b64 s6, s[6:7]
	v_mov_b32_e32 v1, 0x2000
	v_mov_b32_e32 v2, s6
.LBB0_1255:
	s_or_b64 exec, exec, s[8:9]
	s_waitcnt vmcnt(0)

.LBB0_1545:
	s_or_b64 exec, exec, s[6:7]
	s_mov_b64 s[6:7], exec
	v_mbcnt_lo_u32_b32 v1, s6, 0
	v_mbcnt_hi_u32_b32 v1, s7, v1
	v_cmp_eq_u32_e32 vcc, 0, v1
	s_waitcnt vmcnt(0)
	buffer_inv sc1
	s_and_saveexec_b64 s[8:9], vcc
	s_cbranch_execz .LBB0_1547
	s_bcnt1_i32_b64 s6, s[6:7]
	v_mov_b32_e32 v1, 0x2000
	v_mov_b32_e32 v2, s6
.LBB0_1547:
	s_or_b64 exec, exec, s[8:9]
	s_waitcnt vmcnt(0)

.LBB0_1642:
	s_or_b64 exec, exec, s[8:9]
	s_mov_b64 s[8:9], exec
	v_mbcnt_lo_u32_b32 v1, s8, 0
	v_mbcnt_hi_u32_b32 v1, s9, v1
	v_cmp_eq_u32_e32 vcc, 0, v1
	s_waitcnt vmcnt(0)
	buffer_inv sc1
	s_and_saveexec_b64 s[10:11], vcc
	s_cbranch_execz .LBB0_1644
	s_bcnt1_i32_b64 s8, s[8:9]
	v_mov_b32_e32 v1, 0x2000
	v_mov_b32_e32 v2, s8
.LBB0_1644:
	s_or_b64 exec, exec, s[10:11]
	s_waitcnt vmcnt(0)

.LBB0_1721:
	s_or_b64 exec, exec, s[6:7]
	s_mov_b64 s[6:7], exec
	v_mbcnt_lo_u32_b32 v1, s6, 0
	v_mbcnt_hi_u32_b32 v1, s7, v1
	v_cmp_eq_u32_e32 vcc, 0, v1
	s_waitcnt vmcnt(0)
	buffer_inv sc1
	s_and_saveexec_b64 s[8:9], vcc
	s_cbranch_execz .LBB0_1723
	s_bcnt1_i32_b64 s6, s[6:7]
	v_mov_b32_e32 v1, 0x2000
	v_mov_b32_e32 v2, s6
.LBB0_1723:
	s_or_b64 exec, exec, s[8:9]
	s_waitcnt vmcnt(0)
